# v68 + three 4-byte pads so every hot loop head is at 0 mod 8 bytes
# baseline (speedup 1.0000x reference)
.LBB0_47:
	s_or_b64 exec, exec, s[8:9]
	s_load_dword s3, s[0:1], 0x68
	s_cmpk_gt_i32 s12, 0x3fff
	v_mbcnt_lo_u32_b32 v205, -1, 0
	v_cmp_eq_u32_e64 s[0:1], 0, v204
	s_cbranch_scc1 .LBB0_58
	v_mbcnt_hi_u32_b32 v2, -1, v205
	v_and_b32_e32 v1, 64, v2
	s_ashr_i32 s7, s6, 31
	v_add_u32_e32 v3, 64, v1
	v_xor_b32_e32 v1, 1, v2
	s_lshl_b32 s4, s54, 4
	s_mul_i32 s8, s54, 24
	s_ashr_i32 s13, s12, 31
	v_cmp_lt_i32_e32 vcc, v1, v3
	v_xor_b32_e32 v4, 2, v2
	s_ashr_i32 s5, s4, 31
	s_ashr_i32 s9, s8, 31
	s_lshl_b32 s18, s54, 5
	s_lshl_b64 s[20:21], s[6:7], 12
	s_lshl_b64 s[10:11], s[6:7], 11
	s_lshl_b64 s[14:15], s[12:13], 2
	v_cndmask_b32_e32 v1, v2, v1, vcc
	v_cmp_lt_i32_e32 vcc, v4, v3
	s_add_u32 s46, s14, 0x1980000
	s_addc_u32 s47, s15, 0
	v_cndmask_b32_e32 v4, v2, v4, vcc
	s_ashr_i32 s19, s18, 31
	v_lshlrev_b32_e32 v83, 2, v4
	v_xor_b32_e32 v4, 4, v2
	s_lshl_b64 s[28:29], s[18:19], 2
	s_lshl_b64 s[14:15], s[6:7], 2
	v_cmp_lt_i32_e32 vcc, v4, v3
	s_add_u32 s48, s46, s14
	s_addc_u32 s49, s47, s15
	v_cndmask_b32_e32 v4, v2, v4, vcc
	s_lshl_b64 s[4:5], s[4:5], 2
	v_lshlrev_b32_e32 v85, 2, v4
	v_xor_b32_e32 v4, 8, v2
	s_add_u32 s56, s46, s4
	v_cmp_lt_i32_e32 vcc, v4, v3
	s_addc_u32 s57, s47, s5
	s_lshl_b64 s[4:5], s[8:9], 2
	v_cndmask_b32_e32 v4, v2, v4, vcc
	s_add_u32 s60, s46, s4
	v_lshlrev_b32_e32 v87, 2, v4
	v_xor_b32_e32 v4, 16, v2
	s_addc_u32 s61, s47, s5
	s_lshl_b64 s[4:5], s[12:13], 12
	v_cmp_lt_i32_e32 vcc, v4, v3
	s_add_u32 s4, s36, s4
	v_lshlrev_b32_e32 v66, 4, v204
	v_cndmask_b32_e32 v4, v2, v4, vcc
	v_mov_b32_e32 v67, 0
	s_addc_u32 s5, s37, s5
	v_lshlrev_b32_e32 v88, 2, v4
	v_xor_b32_e32 v4, 32, v2
	v_lshl_add_u64 v[70:71], s[4:5], 0, v[66:67]
	s_lshl_b64 s[36:37], s[18:19], 12
	s_lshl_b64 s[4:5], s[12:13], 11
	s_lshl_b64 s[44:45], s[18:19], 11
	v_cmp_lt_i32_e32 vcc, v4, v3
	s_add_u32 s7, s10, s4
	s_addc_u32 s8, s11, s5
	v_cndmask_b32_e32 v2, v2, v4, vcc
	v_lshlrev_b32_e32 v4, 3, v204
	v_lshlrev_b32_e32 v89, 2, v2
	v_or_b32_e32 v2, s7, v4
	v_mov_b32_e32 v3, s8
	s_mov_b64 s[8:9], 0x2000400
	s_add_u32 s7, s20, s4
	v_lshl_add_u64 v[74:75], v[2:3], 0, s[8:9]
	s_addc_u32 s10, s21, s5
	v_or_b32_e32 v2, s7, v4
	s_mul_hi_i32 s7, s6, 0x1800
	s_mulk_i32 s6, 0x1800
	v_or_b32_e32 v72, s4, v4
	s_add_u32 s4, s6, s4
	v_mov_b32_e32 v73, s5
	v_mov_b32_e32 v3, s10
	s_addc_u32 s5, s7, s5
	v_lshl_add_u64 v[76:77], v[2:3], 0, s[8:9]
	v_or_b32_e32 v2, s4, v4
	v_mov_b32_e32 v3, s5
	v_lshlrev_b32_e32 v1, 2, v1
	v_lshl_add_u64 v[68:69], s[38:39], 0, v[66:67]
	v_lshl_add_u64 v[78:79], v[2:3], 0, s[8:9]
	v_mov_b32_e32 v90, 0x358637bd
	s_mov_b32 s13, 0xf800000
	v_mov_b32_e32 v91, 0x260
	s_movk_i32 s19, 0x7fff
	s_mov_b32 s62, 0xffff0000
	s_brev_b32 s63, 64
	global_load_dwordx4 v[120:123], v[68:69], off
	global_load_dwordx4 v[124:127], v[68:69], off offset:1024
	global_load_dwordx4 v[128:131], v[68:69], off offset:2048
	global_load_dwordx4 v[132:135], v[68:69], off offset:3072
	s_nop 0
	s_branch .LBB0_50

.LBB0_227:
	s_nop 0
	v_lshrrev_b32_e32 v1, 8, v196
	v_lshlrev_b32_e32 v0, 2, v196
	v_and_b32_e32 v0, 0x3fc, v0
	v_mov_b32_e32 v21, 0
	v_lshlrev_b32_e32 v20, 12, v1
	v_lshl_add_u64 v[2:3], s[36:37], 0, v[20:21]
	v_lshlrev_b32_e32 v20, 2, v0
	v_lshl_add_u64 v[24:25], s[42:43], 0, v[20:21]
	s_mov_b64 s[0:1], 0x1000
	v_lshl_add_u64 v[22:23], v[2:3], 0, v[20:21]
	v_lshl_add_u64 v[26:27], v[24:25], 0, s[0:1]
	s_mov_b64 s[0:1], 0x2000
	v_lshlrev_b32_e32 v20, 11, v1
	s_ashr_i32 s3, s2, 31
	v_lshl_add_u64 v[28:29], v[24:25], 0, s[0:1]
	s_movk_i32 s0, 0x100
	v_lshl_add_u64 v[2:3], s[28:29], 0, v[20:21]
	v_lshlrev_b32_e32 v20, 1, v0
	s_ashr_i32 s80, s54, 31
	s_mov_b32 s81, s54
	v_cmp_gt_u32_e64 s[0:1], s0, v196
	v_lshl_add_u64 v[30:31], v[2:3], 0, v[20:21]
	v_mov_b64_e32 v[32:33], 0x100
	v_mov_b64_e32 v[34:35], 0xff
	s_mov_b32 s7, 0
	s_movk_i32 s14, 0x7fff
	s_mov_b32 s15, 0xffff0000
	v_lshlrev_b32_e32 v20, 2, v0
	s_mov_b64 s[8:9], s[2:3]
	s_waitcnt lgkmcnt(0)
	s_branch .LBB0_231

.LBB0_741:
	s_nop 0
	s_waitcnt lgkmcnt(0)
	s_and_b64 vcc, exec, s[6:7]
	v_readfirstlane_b32 s8, v196
	s_cbranch_vccnz .LBB0_765
	s_lshr_b32 s0, s3, 29
	s_add_i32 s6, s2, s0
	s_and_b32 s0, s6, -8
	s_sub_i32 s5, s2, s0
	s_cmp_gt_i32 s5, -1
	s_cbranch_scc0 .LBB0_744
	s_lshl_b32 s4, s5, 5
	s_ashr_i32 s0, s6, 3
	s_cbranch_execz .LBB0_745
	s_branch .LBB0_746
